# attention tiles: softmax VALU spread evenly over PV MFMA gaps (3-4 per gap), half-0 softmax starts after the second half-1 QK MFMA
# speedup vs baseline: 1.0116x; 1.0074x over previous
.Lu884:
	s_add_u32 s72, s8, s0
	s_addc_u32 s73, s9, s1
	s_add_u32 m0, s74, 0x6000
	s_nop 0
	global_load_lds_dwordx4 v164, s[72:73]
	s_add_u32 m0, s74, 0x8000
	s_nop 0
	global_load_lds_dwordx4 v170, s[72:73]
	s_add_u32 m0, s74, 0xa000
	s_nop 0
	global_load_lds_dwordx4 v168, s[72:73]
	s_cmp_gt_u32 s57, s75
	s_cbranch_scc1 .Lu888
	ds_read_b128 v[146:149], v198
	ds_read_b128 v[150:153], v171
	ds_read_b128 v[246:249], v174
	ds_read_b128 v[250:253], v175
	ds_read_b128 v[180:183], v176
	ds_read_b128 v[184:187], v177
	s_waitcnt lgkmcnt(5)
	v_mfma_f32_32x32x16_bf16 v[82:97], v[146:149], v[98:101], v[210:225]
	ds_read_b128 v[146:149], v178
	s_waitcnt lgkmcnt(5)
	v_mfma_f32_32x32x16_bf16 v[82:97], v[150:153], v[102:105], v[82:97]
	ds_read_b128 v[150:153], v179
	s_waitcnt lgkmcnt(5)
	v_mfma_f32_32x32x16_bf16 v[82:97], v[246:249], v[106:109], v[82:97]
	ds_read_b128 v[246:249], v199
	s_waitcnt lgkmcnt(5)
	v_mfma_f32_32x32x16_bf16 v[82:97], v[250:253], v[110:113], v[82:97]
	ds_read_b128 v[250:253], v202
	s_waitcnt lgkmcnt(5)
	v_mfma_f32_32x32x16_bf16 v[82:97], v[180:183], v[122:125], v[82:97]
	ds_read_b128 v[180:183], v207
	s_waitcnt lgkmcnt(5)
	v_mfma_f32_32x32x16_bf16 v[82:97], v[184:187], v[114:117], v[82:97]
	ds_read_b128 v[184:187], v208
	s_waitcnt lgkmcnt(5)
	v_mfma_f32_32x32x16_bf16 v[82:97], v[146:149], v[118:121], v[82:97]
	ds_read_b128 v[146:149], v198 offset:8192
	s_waitcnt lgkmcnt(5)
	v_mfma_f32_32x32x16_bf16 v[82:97], v[150:153], v[126:129], v[82:97]
	ds_read_b128 v[150:153], v171 offset:8192
	s_waitcnt lgkmcnt(5)
	v_mfma_f32_32x32x16_bf16 v[82:97], v[246:249], v[130:133], v[82:97]
	ds_read_b128 v[246:249], v174 offset:8192
	s_waitcnt lgkmcnt(5)
	v_mfma_f32_32x32x16_bf16 v[82:97], v[250:253], v[134:137], v[82:97]
	ds_read_b128 v[250:253], v175 offset:8192
	s_waitcnt lgkmcnt(5)
	v_mfma_f32_32x32x16_bf16 v[82:97], v[180:183], v[138:141], v[82:97]
	ds_read_b128 v[180:183], v176 offset:8192
	s_waitcnt lgkmcnt(5)
	v_mfma_f32_32x32x16_bf16 v[82:97], v[184:187], v[142:145], v[82:97]
	ds_read_b128 v[184:187], v177 offset:8192
	ds_read_b64_tr_b16 v[238:239], v188 offset:0
	ds_read_b64_tr_b16 v[240:241], v189 offset:0
	s_waitcnt lgkmcnt(7)
	v_mfma_f32_32x32x16_bf16 v[66:81], v[146:149], v[98:101], v[210:225]
	ds_read_b128 v[146:149], v178 offset:8192
	ds_read_b64_tr_b16 v[234:235], v192 offset:0
	ds_read_b64_tr_b16 v[236:237], v193 offset:0
	s_waitcnt lgkmcnt(9)
	v_mfma_f32_32x32x16_bf16 v[66:81], v[150:153], v[102:105], v[66:81]
	ds_read_b128 v[150:153], v179 offset:8192
	ds_read_b64_tr_b16 v[230:231], v194 offset:0
	ds_read_b64_tr_b16 v[232:233], v195 offset:0
	v_exp_f32_e32 v82, v82
	v_exp_f32_e32 v83, v83
	v_exp_f32_e32 v84, v84
	v_add_f32_e32 v173, v173, v82
	s_waitcnt lgkmcnt(11)
	v_mfma_f32_32x32x16_bf16 v[66:81], v[246:249], v[106:109], v[66:81]
	ds_read_b128 v[246:249], v199 offset:4096
	ds_read_b64_tr_b16 v[226:227], v196 offset:0
	ds_read_b64_tr_b16 v[228:229], v197 offset:0
	v_exp_f32_e32 v85, v85
	v_mov_b32_e32 v242, v83
	v_cvt_pk_bf16_f32 v82, v82, v83
	v_exp_f32_e32 v86, v86
	s_waitcnt lgkmcnt(13)
	v_mfma_f32_32x32x16_bf16 v[66:81], v[250:253], v[110:113], v[66:81]
	ds_read_b128 v[250:253], v202 offset:4096
	v_add_f32_e32 v173, v173, v84
	v_exp_f32_e32 v87, v87
	v_add_f32_e32 v242, v242, v85
	v_cvt_pk_bf16_f32 v83, v84, v85
	s_waitcnt lgkmcnt(13)
	v_mfma_f32_32x32x16_bf16 v[66:81], v[180:183], v[122:125], v[66:81]
	ds_read_b128 v[180:183], v207 offset:4096
	v_exp_f32_e32 v88, v88
	v_add_f32_e32 v173, v173, v86
	v_exp_f32_e32 v89, v89
	v_add_f32_e32 v242, v242, v87
	s_waitcnt lgkmcnt(13)
	v_mfma_f32_32x32x16_bf16 v[66:81], v[184:187], v[114:117], v[66:81]
	ds_read_b128 v[184:187], v208 offset:4096
	v_cvt_pk_bf16_f32 v84, v86, v87
	v_add_f32_e32 v173, v173, v88
	v_add_f32_e32 v242, v242, v89
	v_cvt_pk_bf16_f32 v85, v88, v89
	s_waitcnt lgkmcnt(11)
	v_mfma_f32_32x32x16_bf16 v[66:81], v[146:149], v[118:121], v[66:81]
	v_exp_f32_e32 v90, v90
	v_exp_f32_e32 v91, v91
	v_exp_f32_e32 v92, v92
	v_add_f32_e32 v173, v173, v90
	s_waitcnt lgkmcnt(8)
	v_mfma_f32_32x32x16_bf16 v[66:81], v[150:153], v[126:129], v[66:81]
	v_exp_f32_e32 v93, v93
	v_add_f32_e32 v242, v242, v91
	v_cvt_pk_bf16_f32 v90, v90, v91
	v_exp_f32_e32 v94, v94
	s_waitcnt lgkmcnt(5)
	v_mfma_f32_32x32x16_bf16 v[66:81], v[246:249], v[130:133], v[66:81]
	v_add_f32_e32 v173, v173, v92
	v_exp_f32_e32 v95, v95
	v_add_f32_e32 v242, v242, v93
	s_waitcnt lgkmcnt(2)
	v_mfma_f32_32x32x16_bf16 v[66:81], v[250:253], v[134:137], v[66:81]
	v_cvt_pk_bf16_f32 v91, v92, v93
	v_exp_f32_e32 v96, v96
	v_add_f32_e32 v173, v173, v94
	s_waitcnt lgkmcnt(1)
	v_mfma_f32_32x32x16_bf16 v[66:81], v[180:183], v[138:141], v[66:81]
	v_exp_f32_e32 v97, v97
	v_add_f32_e32 v242, v242, v95
	v_cvt_pk_bf16_f32 v92, v94, v95
	s_waitcnt lgkmcnt(0)
	v_mfma_f32_32x32x16_bf16 v[66:81], v[184:187], v[142:145], v[66:81]
	v_add_f32_e32 v173, v173, v96
	v_add_f32_e32 v242, v242, v97
	v_cvt_pk_bf16_f32 v93, v96, v97
	ds_read_b64_tr_b16 v[158:159], v188 offset:0x1000
	ds_read_b64_tr_b16 v[160:161], v189 offset:0x1000
	ds_read_b64_tr_b16 v[154:155], v192 offset:0x1000
	ds_read_b64_tr_b16 v[156:157], v193 offset:0x1000
	ds_read_b64_tr_b16 v[150:151], v194 offset:0x1000
	ds_read_b64_tr_b16 v[152:153], v195 offset:0x1000
	ds_read_b64_tr_b16 v[146:147], v196 offset:0x1000
	ds_read_b64_tr_b16 v[148:149], v197 offset:0x1000
	v_mfma_f32_32x32x16_bf16 v[50:65], v[238:241], v[82:85], v[50:65]
	v_mfma_f32_32x32x16_bf16 v[34:49], v[234:237], v[82:85], v[34:49]
	v_exp_f32_e32 v66, v66
	v_exp_f32_e32 v67, v67
	v_exp_f32_e32 v68, v68
	v_add_f32_e32 v173, v173, v66
	v_mfma_f32_32x32x16_bf16 v[18:33], v[230:233], v[82:85], v[18:33]
	v_exp_f32_e32 v69, v69
	v_add_f32_e32 v242, v242, v67
	v_cvt_pk_bf16_f32 v66, v66, v67
	v_exp_f32_e32 v70, v70
	v_mfma_f32_32x32x16_bf16 v[2:17], v[226:229], v[82:85], v[2:17]
	v_add_f32_e32 v173, v173, v68
	v_exp_f32_e32 v71, v71
	v_add_f32_e32 v242, v242, v69
	ds_read_b64_tr_b16 v[238:239], v188 offset:0x2000
	ds_read_b64_tr_b16 v[240:241], v189 offset:0x2000
	ds_read_b64_tr_b16 v[234:235], v192 offset:0x2000
	ds_read_b64_tr_b16 v[236:237], v193 offset:0x2000
	ds_read_b64_tr_b16 v[230:231], v194 offset:0x2000
	ds_read_b64_tr_b16 v[232:233], v195 offset:0x2000
	ds_read_b64_tr_b16 v[226:227], v196 offset:0x2000
	ds_read_b64_tr_b16 v[228:229], v197 offset:0x2000
	s_waitcnt lgkmcnt(8)
	v_mfma_f32_32x32x16_bf16 v[50:65], v[158:161], v[90:93], v[50:65]
	v_cvt_pk_bf16_f32 v67, v68, v69
	v_exp_f32_e32 v72, v72
	v_add_f32_e32 v173, v173, v70
	v_exp_f32_e32 v73, v73
	v_mfma_f32_32x32x16_bf16 v[34:49], v[154:157], v[90:93], v[34:49]
	v_add_f32_e32 v242, v242, v71
	v_cvt_pk_bf16_f32 v68, v70, v71
	v_add_f32_e32 v173, v173, v72
	v_mfma_f32_32x32x16_bf16 v[18:33], v[150:153], v[90:93], v[18:33]
	v_add_f32_e32 v242, v242, v73
	v_cvt_pk_bf16_f32 v69, v72, v73
	v_exp_f32_e32 v74, v74
	v_mfma_f32_32x32x16_bf16 v[2:17], v[146:149], v[90:93], v[2:17]
	v_exp_f32_e32 v75, v75
	v_exp_f32_e32 v76, v76
	v_add_f32_e32 v173, v173, v74
	ds_read_b64_tr_b16 v[158:159], v188 offset:0x3000
	ds_read_b64_tr_b16 v[160:161], v189 offset:0x3000
	ds_read_b64_tr_b16 v[154:155], v192 offset:0x3000
	ds_read_b64_tr_b16 v[156:157], v193 offset:0x3000
	ds_read_b64_tr_b16 v[150:151], v194 offset:0x3000
	ds_read_b64_tr_b16 v[152:153], v195 offset:0x3000
	ds_read_b64_tr_b16 v[146:147], v196 offset:0x3000
	ds_read_b64_tr_b16 v[148:149], v197 offset:0x3000
	s_waitcnt lgkmcnt(8)
	v_mfma_f32_32x32x16_bf16 v[50:65], v[238:241], v[66:69], v[50:65]
	v_exp_f32_e32 v77, v77
	v_add_f32_e32 v242, v242, v75
	v_cvt_pk_bf16_f32 v74, v74, v75
	v_exp_f32_e32 v78, v78
	v_mfma_f32_32x32x16_bf16 v[34:49], v[234:237], v[66:69], v[34:49]
	v_add_f32_e32 v173, v173, v76
	v_exp_f32_e32 v79, v79
	v_add_f32_e32 v242, v242, v77
	v_cvt_pk_bf16_f32 v75, v76, v77
	v_mfma_f32_32x32x16_bf16 v[18:33], v[230:233], v[66:69], v[18:33]
	v_exp_f32_e32 v80, v80
	v_add_f32_e32 v173, v173, v78
	v_exp_f32_e32 v81, v81
	v_add_f32_e32 v242, v242, v79
	v_mfma_f32_32x32x16_bf16 v[2:17], v[226:229], v[66:69], v[2:17]
	v_cvt_pk_bf16_f32 v76, v78, v79
	v_add_f32_e32 v173, v173, v80
	v_add_f32_e32 v242, v242, v81
	v_cvt_pk_bf16_f32 v77, v80, v81
	s_waitcnt lgkmcnt(0)
	v_add_f32_e32 v173, v173, v242
	v_mfma_f32_32x32x16_bf16 v[50:65], v[158:161], v[74:77], v[50:65]
	v_mfma_f32_32x32x16_bf16 v[34:49], v[154:157], v[74:77], v[34:49]
	v_mfma_f32_32x32x16_bf16 v[18:33], v[150:153], v[74:77], v[18:33]
	v_mfma_f32_32x32x16_bf16 v[2:17], v[146:149], v[74:77], v[2:17]

.Lu890:
	s_cmp_ge_u32 s57, s75
	s_cbranch_scc1 .Lu883
	ds_read_b128 v[146:149], v198 offset:24576
	ds_read_b128 v[150:153], v171 offset:24576
	ds_read_b128 v[246:249], v174 offset:24576
	ds_read_b128 v[250:253], v175 offset:24576
	ds_read_b128 v[180:183], v176 offset:24576
	ds_read_b128 v[184:187], v177 offset:24576
	s_waitcnt lgkmcnt(5)
	v_mfma_f32_32x32x16_bf16 v[82:97], v[146:149], v[98:101], v[210:225]
	ds_read_b128 v[146:149], v178 offset:24576
	s_waitcnt lgkmcnt(5)
	v_mfma_f32_32x32x16_bf16 v[82:97], v[150:153], v[102:105], v[82:97]
	ds_read_b128 v[150:153], v179 offset:24576
	s_waitcnt lgkmcnt(5)
	v_mfma_f32_32x32x16_bf16 v[82:97], v[246:249], v[106:109], v[82:97]
	ds_read_b128 v[246:249], v199 offset:24576
	s_waitcnt lgkmcnt(5)
	v_mfma_f32_32x32x16_bf16 v[82:97], v[250:253], v[110:113], v[82:97]
	ds_read_b128 v[250:253], v202 offset:24576
	s_waitcnt lgkmcnt(5)
	v_mfma_f32_32x32x16_bf16 v[82:97], v[180:183], v[122:125], v[82:97]
	ds_read_b128 v[180:183], v207 offset:24576
	s_waitcnt lgkmcnt(5)
	v_mfma_f32_32x32x16_bf16 v[82:97], v[184:187], v[114:117], v[82:97]
	ds_read_b128 v[184:187], v208 offset:24576
	s_waitcnt lgkmcnt(5)
	v_mfma_f32_32x32x16_bf16 v[82:97], v[146:149], v[118:121], v[82:97]
	ds_read_b128 v[146:149], v198 offset:32768
	s_waitcnt lgkmcnt(5)
	v_mfma_f32_32x32x16_bf16 v[82:97], v[150:153], v[126:129], v[82:97]
	ds_read_b128 v[150:153], v171 offset:32768
	s_waitcnt lgkmcnt(5)
	v_mfma_f32_32x32x16_bf16 v[82:97], v[246:249], v[130:133], v[82:97]
	ds_read_b128 v[246:249], v174 offset:32768
	s_waitcnt lgkmcnt(5)
	v_mfma_f32_32x32x16_bf16 v[82:97], v[250:253], v[134:137], v[82:97]
	ds_read_b128 v[250:253], v175 offset:32768
	s_waitcnt lgkmcnt(5)
	v_mfma_f32_32x32x16_bf16 v[82:97], v[180:183], v[138:141], v[82:97]
	ds_read_b128 v[180:183], v176 offset:32768
	s_waitcnt lgkmcnt(5)
	v_mfma_f32_32x32x16_bf16 v[82:97], v[184:187], v[142:145], v[82:97]
	ds_read_b128 v[184:187], v177 offset:32768
	ds_read_b64_tr_b16 v[238:239], v188 offset:0x6000
	ds_read_b64_tr_b16 v[240:241], v189 offset:0x6000
	s_waitcnt lgkmcnt(7)
	v_mfma_f32_32x32x16_bf16 v[66:81], v[146:149], v[98:101], v[210:225]
	ds_read_b128 v[146:149], v178 offset:32768
	ds_read_b64_tr_b16 v[234:235], v192 offset:0x6000
	ds_read_b64_tr_b16 v[236:237], v193 offset:0x6000
	s_waitcnt lgkmcnt(9)
	v_mfma_f32_32x32x16_bf16 v[66:81], v[150:153], v[102:105], v[66:81]
	ds_read_b128 v[150:153], v179 offset:32768
	ds_read_b64_tr_b16 v[230:231], v194 offset:0x6000
	ds_read_b64_tr_b16 v[232:233], v195 offset:0x6000
	v_exp_f32_e32 v82, v82
	v_exp_f32_e32 v83, v83
	v_exp_f32_e32 v84, v84
	v_add_f32_e32 v173, v173, v82
	s_waitcnt lgkmcnt(11)
	v_mfma_f32_32x32x16_bf16 v[66:81], v[246:249], v[106:109], v[66:81]
	ds_read_b128 v[246:249], v199 offset:28672
	ds_read_b64_tr_b16 v[226:227], v196 offset:0x6000
	ds_read_b64_tr_b16 v[228:229], v197 offset:0x6000
	v_exp_f32_e32 v85, v85
	v_mov_b32_e32 v242, v83
	v_cvt_pk_bf16_f32 v82, v82, v83
	v_exp_f32_e32 v86, v86
	s_waitcnt lgkmcnt(13)
	v_mfma_f32_32x32x16_bf16 v[66:81], v[250:253], v[110:113], v[66:81]
	ds_read_b128 v[250:253], v202 offset:28672
	v_add_f32_e32 v173, v173, v84
	v_exp_f32_e32 v87, v87
	v_add_f32_e32 v242, v242, v85
	v_cvt_pk_bf16_f32 v83, v84, v85
	s_waitcnt lgkmcnt(13)
	v_mfma_f32_32x32x16_bf16 v[66:81], v[180:183], v[122:125], v[66:81]
	ds_read_b128 v[180:183], v207 offset:28672
	v_exp_f32_e32 v88, v88
	v_add_f32_e32 v173, v173, v86
	v_exp_f32_e32 v89, v89
	v_add_f32_e32 v242, v242, v87
	s_waitcnt lgkmcnt(13)
	v_mfma_f32_32x32x16_bf16 v[66:81], v[184:187], v[114:117], v[66:81]
	ds_read_b128 v[184:187], v208 offset:28672
	v_cvt_pk_bf16_f32 v84, v86, v87
	v_add_f32_e32 v173, v173, v88
	v_add_f32_e32 v242, v242, v89
	v_cvt_pk_bf16_f32 v85, v88, v89
	s_waitcnt lgkmcnt(11)
	v_mfma_f32_32x32x16_bf16 v[66:81], v[146:149], v[118:121], v[66:81]
	v_exp_f32_e32 v90, v90
	v_exp_f32_e32 v91, v91
	v_exp_f32_e32 v92, v92
	v_add_f32_e32 v173, v173, v90
	s_waitcnt lgkmcnt(8)
	v_mfma_f32_32x32x16_bf16 v[66:81], v[150:153], v[126:129], v[66:81]
	v_exp_f32_e32 v93, v93
	v_add_f32_e32 v242, v242, v91
	v_cvt_pk_bf16_f32 v90, v90, v91
	v_exp_f32_e32 v94, v94
	s_waitcnt lgkmcnt(5)
	v_mfma_f32_32x32x16_bf16 v[66:81], v[246:249], v[130:133], v[66:81]
	v_add_f32_e32 v173, v173, v92
	v_exp_f32_e32 v95, v95
	v_add_f32_e32 v242, v242, v93
	s_waitcnt lgkmcnt(2)
	v_mfma_f32_32x32x16_bf16 v[66:81], v[250:253], v[134:137], v[66:81]
	v_cvt_pk_bf16_f32 v91, v92, v93
	v_exp_f32_e32 v96, v96
	v_add_f32_e32 v173, v173, v94
	s_waitcnt lgkmcnt(1)
	v_mfma_f32_32x32x16_bf16 v[66:81], v[180:183], v[138:141], v[66:81]
	v_exp_f32_e32 v97, v97
	v_add_f32_e32 v242, v242, v95
	v_cvt_pk_bf16_f32 v92, v94, v95
	s_waitcnt lgkmcnt(0)
	v_mfma_f32_32x32x16_bf16 v[66:81], v[184:187], v[142:145], v[66:81]
	v_add_f32_e32 v173, v173, v96
	v_add_f32_e32 v242, v242, v97
	v_cvt_pk_bf16_f32 v93, v96, v97
	ds_read_b64_tr_b16 v[158:159], v188 offset:0x7000
	ds_read_b64_tr_b16 v[160:161], v189 offset:0x7000
	ds_read_b64_tr_b16 v[154:155], v192 offset:0x7000
	ds_read_b64_tr_b16 v[156:157], v193 offset:0x7000
	ds_read_b64_tr_b16 v[150:151], v194 offset:0x7000
	ds_read_b64_tr_b16 v[152:153], v195 offset:0x7000
	ds_read_b64_tr_b16 v[146:147], v196 offset:0x7000
	ds_read_b64_tr_b16 v[148:149], v197 offset:0x7000
	v_mfma_f32_32x32x16_bf16 v[50:65], v[238:241], v[82:85], v[50:65]
	v_mfma_f32_32x32x16_bf16 v[34:49], v[234:237], v[82:85], v[34:49]
	v_exp_f32_e32 v66, v66
	v_exp_f32_e32 v67, v67
	v_exp_f32_e32 v68, v68
	v_add_f32_e32 v173, v173, v66
	v_mfma_f32_32x32x16_bf16 v[18:33], v[230:233], v[82:85], v[18:33]
	v_exp_f32_e32 v69, v69
	v_add_f32_e32 v242, v242, v67
	v_cvt_pk_bf16_f32 v66, v66, v67
	v_exp_f32_e32 v70, v70
	v_mfma_f32_32x32x16_bf16 v[2:17], v[226:229], v[82:85], v[2:17]
	v_add_f32_e32 v173, v173, v68
	v_exp_f32_e32 v71, v71
	v_add_f32_e32 v242, v242, v69
	ds_read_b64_tr_b16 v[238:239], v188 offset:0x8000
	ds_read_b64_tr_b16 v[240:241], v189 offset:0x8000
	ds_read_b64_tr_b16 v[234:235], v192 offset:0x8000
	ds_read_b64_tr_b16 v[236:237], v193 offset:0x8000
	ds_read_b64_tr_b16 v[230:231], v194 offset:0x8000
	ds_read_b64_tr_b16 v[232:233], v195 offset:0x8000
	ds_read_b64_tr_b16 v[226:227], v196 offset:0x8000
	ds_read_b64_tr_b16 v[228:229], v197 offset:0x8000
	s_waitcnt lgkmcnt(8)
	v_mfma_f32_32x32x16_bf16 v[50:65], v[158:161], v[90:93], v[50:65]
	v_cvt_pk_bf16_f32 v67, v68, v69
	v_exp_f32_e32 v72, v72
	v_add_f32_e32 v173, v173, v70
	v_exp_f32_e32 v73, v73
	v_mfma_f32_32x32x16_bf16 v[34:49], v[154:157], v[90:93], v[34:49]
	v_add_f32_e32 v242, v242, v71
	v_cvt_pk_bf16_f32 v68, v70, v71
	v_add_f32_e32 v173, v173, v72
	v_mfma_f32_32x32x16_bf16 v[18:33], v[150:153], v[90:93], v[18:33]
	v_add_f32_e32 v242, v242, v73
	v_cvt_pk_bf16_f32 v69, v72, v73
	v_exp_f32_e32 v74, v74
	v_mfma_f32_32x32x16_bf16 v[2:17], v[146:149], v[90:93], v[2:17]
	v_exp_f32_e32 v75, v75
	v_exp_f32_e32 v76, v76
	v_add_f32_e32 v173, v173, v74
	ds_read_b64_tr_b16 v[158:159], v188 offset:0x9000
	ds_read_b64_tr_b16 v[160:161], v189 offset:0x9000
	ds_read_b64_tr_b16 v[154:155], v192 offset:0x9000
	ds_read_b64_tr_b16 v[156:157], v193 offset:0x9000
	ds_read_b64_tr_b16 v[150:151], v194 offset:0x9000
	ds_read_b64_tr_b16 v[152:153], v195 offset:0x9000
	ds_read_b64_tr_b16 v[146:147], v196 offset:0x9000
	ds_read_b64_tr_b16 v[148:149], v197 offset:0x9000
	s_waitcnt lgkmcnt(8)
	v_mfma_f32_32x32x16_bf16 v[50:65], v[238:241], v[66:69], v[50:65]
	v_exp_f32_e32 v77, v77
	v_add_f32_e32 v242, v242, v75
	v_cvt_pk_bf16_f32 v74, v74, v75
	v_exp_f32_e32 v78, v78
	v_mfma_f32_32x32x16_bf16 v[34:49], v[234:237], v[66:69], v[34:49]
	v_add_f32_e32 v173, v173, v76
	v_exp_f32_e32 v79, v79
	v_add_f32_e32 v242, v242, v77
	v_cvt_pk_bf16_f32 v75, v76, v77
	v_mfma_f32_32x32x16_bf16 v[18:33], v[230:233], v[66:69], v[18:33]
	v_exp_f32_e32 v80, v80
	v_add_f32_e32 v173, v173, v78
	v_exp_f32_e32 v81, v81
	v_add_f32_e32 v242, v242, v79
	v_mfma_f32_32x32x16_bf16 v[2:17], v[226:229], v[66:69], v[2:17]
	v_cvt_pk_bf16_f32 v76, v78, v79
	v_add_f32_e32 v173, v173, v80
	v_add_f32_e32 v242, v242, v81
	v_cvt_pk_bf16_f32 v77, v80, v81
	s_waitcnt lgkmcnt(0)
	v_add_f32_e32 v173, v173, v242
	v_mfma_f32_32x32x16_bf16 v[50:65], v[158:161], v[74:77], v[50:65]
	v_mfma_f32_32x32x16_bf16 v[34:49], v[154:157], v[74:77], v[34:49]
	v_mfma_f32_32x32x16_bf16 v[18:33], v[150:153], v[74:77], v[18:33]
	v_mfma_f32_32x32x16_bf16 v[2:17], v[146:149], v[74:77], v[2:17]
	s_branch .Lu883
